# P8 conversion: next ticket prefetched (atomic kept in flight across the tile), LDS hand-off via ds_write/ds_read
# speedup vs baseline: 1.0100x; 1.0042x over previous
; DEVINL void phase8(const Params& p) {
;     ...
;   {
;     unsigned* ticket = (unsigned*)(ws + O_BAR);
;     volatile int* slot = (volatile int*)(dynsmem + 120000);
;     for (;;) {
;       if (tid == 0) *slot = (int)atomicAdd(ticket, 1u);
.LBB0_903:
	s_add_u32 s10, s92, 0x10c00000
	s_addc_u32 s11, s93, 0
	s_mov_b64 s[4:5], src_shared_base
	s_add_u32 s8, s92, 0x8c00000
	v_cmp_eq_u32_e32 vcc, 0, v0
	s_addc_u32 s9, s93, 0
	s_mov_b64 s[6:7], 0
	v_mov_b32_e32 v1, 0
	s_add_i32 s3, 16, 0x1d4c0
	s_movk_i32 s4, 0x1800
	s_movk_i32 s18, 0xfff
	s_movk_i32 s19, 0x404
	s_and_saveexec_b64 s[12:13], vcc
	s_cbranch_execz .Lp8_pf
	v_mov_b32_e32 v2, 1
	global_atomic_add v60, v1, v2, s[96:97] sc0
.Lp8_pf:
	s_or_b64 exec, exec, s[12:13]
	s_branch .LBB0_906

; DEVINL void tr_tile(const float* __restrict__ src, int ldsrc, int nvalid, int k0, int n0,
;                     u16* __restrict__ dst, int lddst, int grp, int gstride, int goff) {
;     ...
; #pragma unroll
;   for (int i = 0; i < 8; ++i) {
;     int f = tid + i * 512; int r = f >> 6, c4 = (f & 63) * 4;
;     int n = n0 + c4;
;     v[i] = make_float4(0.f, 0.f, 0.f, 0.f);
;     if (n < nvalid) {
;       const f32x4 q = __builtin_nontemporal_load((const f32x4*)(src + (long)(k0 + r) * ldsrc + n));
;       v[i] = make_float4(q[0], q[1], q[2], q[3]);
;     }
;   }
; #pragma unroll
;   for (int i = 0; i < 8; ++i) {
;     int f = tid + i * 512; int r = f >> 6, c4 = (f & 63) * 4;
;     float* tp = tile + r * 257 + c4;
;     tp[0] = v[i].x; tp[1] = v[i].y; tp[2] = v[i].z; tp[3] = v[i].w;
;   }
; DEVINL void phase8(const Params& p) {
;     ...
;       if (tid == 0) *slot = (int)atomicAdd(ticket, 1u);
;       __syncthreads();
;       const int t = *slot;
;       if (t >= 16 * 128 * 3) break;
;       const int which = t / (16 * 128), r = t % (16 * 128), e = r >> 7, tt = r & 127;
;       if (which < 2) {
;         const float* src = (which ? p.w3 : p.w1) + (long)e * 2048 * 1024;
;         int kt = tt & 31, ntile = tt >> 5;
;         tr_tile(src, 1024, 1024, kt * 64, ntile * 256, (u16*)(ws + O_W13T) + (long)e * 2048 * 2048, 2048, 128, 256, which * 128);
.LBB0_906:
	s_and_saveexec_b64 s[12:13], vcc
	s_cbranch_execz .LBB0_910
	s_waitcnt vmcnt(0)
	v_mov_b32_e32 v0, v60
	v_mov_b32_e32 v2, 1
	global_atomic_add v60, v1, v2, s[96:97] sc0
	v_mov_b32_e32 v2, s3
	ds_write_b32 v2, v0
	s_waitcnt lgkmcnt(0)
.LBB0_910:
	s_or_b64 exec, exec, s[12:13]
	v_mov_b32_e32 v2, s3
	s_waitcnt lgkmcnt(0)
	s_barrier
	ds_read_b32 v3, v2
	s_mov_b64 s[14:15], -1
	s_waitcnt lgkmcnt(0)
	v_cmp_gt_i32_e64 s[0:1], s4, v3
	s_and_saveexec_b64 s[12:13], s[0:1]
	s_cbranch_execz .LBB0_905
	v_ashrrev_i32_e32 v0, 31, v3
	v_lshrrev_b32_e32 v0, 21, v0
	v_add_u32_e32 v0, v3, v0
	v_ashrrev_i32_e32 v4, 11, v0
	v_mul_i32_i24_e32 v0, 0x800, v4
	v_sub_u32_e32 v0, v3, v0
	v_ashrrev_i32_e32 v2, 7, v0
	v_cmp_lt_i32_e64 s[0:1], s18, v3
	v_lshlrev_b32_e32 v5, 6, v0
	s_and_saveexec_b64 s[14:15], s[0:1]
	s_xor_b64 s[0:1], exec, s[14:15]
	s_cbranch_execz .LBB0_913
	v_lshlrev_b32_e32 v0, 4, v0
	v_mov_b32_e32 v48, v189
	v_and_b32_e32 v47, 0x700, v0
	v_mov_b32_e32 v3, v1
	v_lshlrev_b32_e32 v0, 2, v48
	v_and_b32_e32 v36, 0xfc, v0
	v_lshlrev_b64 v[6:7], 23, v[2:3]
	v_and_b32_e32 v46, 0x3c0, v5
	v_or_b32_e32 v0, v36, v47
	v_ashrrev_i32_e32 v37, 6, v48
	v_lshl_add_u64 v[6:7], s[84:85], 0, v[6:7]
	v_lshlrev_b32_e32 v0, 2, v0
	v_add_u32_e32 v4, v37, v46
	v_lshl_add_u64 v[32:33], v[6:7], 0, v[0:1]
	v_ashrrev_i32_e32 v5, 31, v4
	v_add_u32_e32 v0, 0x200, v48
	v_lshlrev_b64 v[4:5], 13, v[4:5]
	v_ashrrev_i32_e32 v38, 6, v0
	v_lshl_add_u64 v[12:13], v[32:33], 0, v[4:5]
	v_add_u32_e32 v4, v38, v46
	v_ashrrev_i32_e32 v5, 31, v4
	v_add_u32_e32 v0, 0x400, v48
	v_lshlrev_b64 v[4:5], 13, v[4:5]
	v_ashrrev_i32_e32 v40, 6, v0
	v_lshl_add_u64 v[14:15], v[32:33], 0, v[4:5]
	global_load_dwordx4 v[4:7], v[12:13], off nt
	global_load_dwordx4 v[8:11], v[14:15], off nt
	v_add_u32_e32 v12, v40, v46
	v_ashrrev_i32_e32 v13, 31, v12
	v_add_u32_e32 v0, 0x600, v48
	v_lshlrev_b64 v[12:13], 13, v[12:13]
	v_ashrrev_i32_e32 v42, 6, v0
	v_lshl_add_u64 v[20:21], v[32:33], 0, v[12:13]
	v_add_u32_e32 v12, v42, v46
	v_ashrrev_i32_e32 v13, 31, v12
	v_add_u32_e32 v0, 0x800, v48
	v_lshlrev_b64 v[12:13], 13, v[12:13]
	v_ashrrev_i32_e32 v44, 6, v0
	v_lshl_add_u64 v[22:23], v[32:33], 0, v[12:13]
	global_load_dwordx4 v[12:15], v[20:21], off nt
	global_load_dwordx4 v[16:19], v[22:23], off nt
	v_add_u32_e32 v20, v44, v46
	v_ashrrev_i32_e32 v21, 31, v20
	v_add_u32_e32 v0, 0xa00, v48
	v_lshlrev_b64 v[20:21], 13, v[20:21]
	v_ashrrev_i32_e32 v49, 6, v0
	v_lshl_add_u64 v[28:29], v[32:33], 0, v[20:21]
	v_add_u32_e32 v20, v49, v46
	v_ashrrev_i32_e32 v21, 31, v20
	v_add_u32_e32 v0, 0xc00, v48
	v_lshlrev_b64 v[20:21], 13, v[20:21]
	v_ashrrev_i32_e32 v50, 6, v0
	v_add_u32_e32 v0, 0xe00, v48
	v_lshl_add_u64 v[30:31], v[32:33], 0, v[20:21]
	global_load_dwordx4 v[20:23], v[28:29], off nt
	global_load_dwordx4 v[24:27], v[30:31], off nt
	v_add_u32_e32 v28, v50, v46
	v_ashrrev_i32_e32 v51, 6, v0
	v_ashrrev_i32_e32 v29, 31, v28
	v_add_u32_e32 v34, v51, v46
	v_lshlrev_b64 v[28:29], 13, v[28:29]
	v_ashrrev_i32_e32 v35, 31, v34
	v_lshl_add_u64 v[28:29], v[32:33], 0, v[28:29]
	v_lshlrev_b64 v[34:35], 13, v[34:35]
	global_load_dwordx4 v[28:31], v[28:29], off nt
	v_lshl_add_u64 v[32:33], v[32:33], 0, v[34:35]
	global_load_dwordx4 v[32:35], v[32:33], off nt
	v_lshl_add_u32 v0, v36, 2, 16
	v_mad_u64_u32 v[36:37], s[14:15], v37, s19, v[0:1]
	v_mad_u64_u32 v[38:39], s[14:15], v38, s19, v[0:1]
	v_mad_u64_u32 v[40:41], s[14:15], v40, s19, v[0:1]
	v_mad_u64_u32 v[42:43], s[14:15], v42, s19, v[0:1]
	v_mad_u64_u32 v[44:45], s[14:15], v44, s19, v[0:1]
	v_lshlrev_b64 v[2:3], 22, v[2:3]
	v_lshl_add_u64 v[2:3], s[10:11], 0, v[2:3]
	s_waitcnt vmcnt(7)
	ds_write2_b32 v36, v4, v5 offset1:1
	ds_write2_b32 v36, v6, v7 offset0:2 offset1:3
	s_waitcnt vmcnt(6)
	ds_write2_b32 v38, v8, v9 offset1:1
	ds_write2_b32 v38, v10, v11 offset0:2 offset1:3
	s_waitcnt vmcnt(5)
	ds_write2_b32 v40, v12, v13 offset1:1
	ds_write2_b32 v40, v14, v15 offset0:2 offset1:3
	s_waitcnt vmcnt(4)
	ds_write2_b32 v42, v16, v17 offset1:1
	ds_write2_b32 v42, v18, v19 offset0:2 offset1:3
	s_waitcnt vmcnt(3)
	ds_write2_b32 v44, v20, v21 offset1:1
	ds_write2_b32 v44, v22, v23 offset0:2 offset1:3
	v_mad_u64_u32 v[4:5], s[14:15], v49, s19, v[0:1]
	s_waitcnt vmcnt(2)
	ds_write2_b32 v4, v24, v25 offset1:1
	ds_write2_b32 v4, v26, v27 offset0:2 offset1:3
	v_mad_u64_u32 v[4:5], s[14:15], v50, s19, v[0:1]
	s_waitcnt vmcnt(1)
	ds_write2_b32 v4, v28, v29 offset1:1
	ds_write2_b32 v4, v30, v31 offset0:2 offset1:3
	v_mad_u64_u32 v[4:5], s[14:15], v51, s19, v[0:1]
	s_waitcnt vmcnt(0)
	ds_write2_b32 v4, v32, v33 offset1:1
	ds_write2_b32 v4, v34, v35 offset0:2 offset1:3
	v_lshlrev_b32_e32 v4, 5, v48
	v_ashrrev_i32_e32 v0, 1, v48
	v_and_b32_e32 v6, 32, v4
	v_mul_u32_u24_e32 v4, 0x404, v6
	v_lshlrev_b32_e32 v5, 2, v0
	v_add_u32_e32 v0, v0, v47
	v_add3_u32 v8, 16, v4, v5
	v_ashrrev_i32_e32 v4, 31, v0
	v_lshrrev_b32_e32 v4, 2, v4
	v_add_u32_e32 v4, v0, v4
	v_and_b32_e32 v4, -2.0, v4
	v_sub_u32_e32 v4, v0, v4
	v_ashrrev_i32_e32 v5, 31, v4
	v_lshlrev_b64 v[4:5], 11, v[4:5]
	s_waitcnt lgkmcnt(0)
	s_barrier
; DEVINL void tr_tile(const float* __restrict__ src, int ldsrc, int nvalid, int k0, int n0,
;                     u16* __restrict__ dst, int lddst, int grp, int gstride, int goff) {
;     ...
;   {
;     const int n = tid >> 1, kc = (tid & 1) * 32;
;     const float* tp = tile + kc * 257 + n;
;     const int nn = n0 + n;
;     const long row = (long)(nn / grp) * gstride + (nn % grp) + goff;
;     uint4* dp = (uint4*)(dst + row * lddst + k0 + kc);
; #pragma unroll
;     for (int q = 0; q < 4; ++q) {
;       uint4 o;
;       o.x = pk2(tp[(q * 8 + 0) * 257], tp[(q * 8 + 1) * 257]);
;       o.y = pk2(tp[(q * 8 + 2) * 257], tp[(q * 8 + 3) * 257]);
;       o.z = pk2(tp[(q * 8 + 4) * 257], tp[(q * 8 + 5) * 257]);
;       o.w = pk2(tp[(q * 8 + 6) * 257], tp[(q * 8 + 7) * 257]);
;       dp[q] = o;
;     }
;   }
	v_lshl_add_u64 v[2:3], v[2:3], 0, v[4:5]
	ds_read_b32 v4, v8
	ds_read_b32 v5, v8 offset:1028
	ds_read_b32 v9, v8 offset:2056
	ds_read_b32 v10, v8 offset:3084
	ds_read_b32 v11, v8 offset:4112
	ds_read_b32 v12, v8 offset:5140
	ds_read_b32 v13, v8 offset:6168
	ds_read_b32 v14, v8 offset:7196
	v_lshlrev_b32_e32 v0, 1, v46
	v_lshl_add_u64 v[2:3], v[2:3], 0, v[0:1]
	v_lshlrev_b32_e32 v0, 1, v6
	v_lshl_add_u64 v[6:7], v[2:3], 0, v[0:1]
	s_waitcnt lgkmcnt(6)
	v_cvt_pk_bf16_f32 v2, v4, v5
	s_waitcnt lgkmcnt(4)
	v_cvt_pk_bf16_f32 v3, v9, v10
	s_waitcnt lgkmcnt(2)
	v_cvt_pk_bf16_f32 v4, v11, v12
	s_waitcnt lgkmcnt(0)
	v_cvt_pk_bf16_f32 v5, v13, v14
	ds_read_b32 v0, v8 offset:8224
	ds_read_b32 v9, v8 offset:9252
	ds_read_b32 v10, v8 offset:10280
	ds_read_b32 v11, v8 offset:11308
	ds_read_b32 v12, v8 offset:12336
	ds_read_b32 v13, v8 offset:13364
	ds_read_b32 v14, v8 offset:14392
	ds_read_b32 v15, v8 offset:15420
	global_store_dwordx4 v[6:7], v[2:5], off
	s_waitcnt lgkmcnt(6)
	s_nop 0
	v_cvt_pk_bf16_f32 v2, v0, v9
	s_waitcnt lgkmcnt(4)
	v_cvt_pk_bf16_f32 v3, v10, v11
	s_waitcnt lgkmcnt(2)
	v_cvt_pk_bf16_f32 v4, v12, v13
	s_waitcnt lgkmcnt(0)
	v_cvt_pk_bf16_f32 v5, v14, v15
	ds_read_b32 v0, v8 offset:16448
	ds_read_b32 v9, v8 offset:17476
	ds_read_b32 v10, v8 offset:18504
	ds_read_b32 v11, v8 offset:19532
	ds_read_b32 v12, v8 offset:20560
	ds_read_b32 v13, v8 offset:21588
	ds_read_b32 v14, v8 offset:22616
	ds_read_b32 v15, v8 offset:23644
	global_store_dwordx4 v[6:7], v[2:5], off offset:16
	s_waitcnt lgkmcnt(6)
	s_nop 0
	v_cvt_pk_bf16_f32 v2, v0, v9
	s_waitcnt lgkmcnt(4)
	v_cvt_pk_bf16_f32 v3, v10, v11
	s_waitcnt lgkmcnt(2)
	v_cvt_pk_bf16_f32 v4, v12, v13
	s_waitcnt lgkmcnt(0)
	v_cvt_pk_bf16_f32 v5, v14, v15
	ds_read_b32 v0, v8 offset:24672
	ds_read_b32 v9, v8 offset:25700
	ds_read_b32 v10, v8 offset:26728
	ds_read_b32 v11, v8 offset:27756
	ds_read_b32 v12, v8 offset:28784
	ds_read_b32 v13, v8 offset:29812
	ds_read_b32 v14, v8 offset:30840
	ds_read_b32 v8, v8 offset:31868
	global_store_dwordx4 v[6:7], v[2:5], off offset:32
	s_waitcnt lgkmcnt(6)
	s_nop 0
	v_cvt_pk_bf16_f32 v2, v0, v9
	s_waitcnt lgkmcnt(4)
	v_cvt_pk_bf16_f32 v3, v10, v11
	s_waitcnt lgkmcnt(2)
	v_cvt_pk_bf16_f32 v4, v12, v13
	s_waitcnt lgkmcnt(0)
	v_cvt_pk_bf16_f32 v5, v14, v8
	global_store_dwordx4 v[6:7], v[2:5], off offset:48
	s_barrier
